# P0a weight conversion: hand-written 64x64-tile transposer (dwordx4 loads, gain applied after LDS transpose) replaces the per-dword-load transposes
# speedup vs baseline: 1.0177x; 1.0148x over previous
; __device__ __forceinline__ unsigned cvt_pk_bf16(float lo, float hi) { unsigned r; asm volatile("v_cvt_pk_bf16_f32 %0, %1, %2" : "=v"(r) : "v"(lo), "v"(hi)); return r; }
; #define LDS_FENCE() asm volatile("s_waitcnt lgkmcnt(0)" ::: "memory")
; __device__ __forceinline__ void transpose_item(const float* __restrict__ W, int ldw, int K, int N, const float* __restrict__ g, bf16_t* __restrict__ WT, float* scr, int item, int lane) {
;     const int nblk = N / 32, kb = item / nblk, nb = item - kb * nblk, k0 = 64 * kb, n0 = 32 * nb;
; #pragma unroll 8
;     for (int i = 0; i < 32; ++i) { const int kk = 2 * i + (lane >> 5); float v = W[(size_t)(k0 + kk) * ldw + n0 + (lane & 31)]; if (g) v *= g[k0 + kk]; scr[kk * 33 + (lane & 31)] = v; }
;     LDS_FENCE();
;     const int c = lane & 7;
; #pragma unroll
;     for (int j = 0; j < 4; ++j) { const int n = (lane >> 3) + 8 * j; const float* s = scr + (8 * c) * 33 + n;
;         u32x4 o; o.x = cvt_pk_bf16(s[0 * 33], s[1 * 33]); o.y = cvt_pk_bf16(s[2 * 33], s[3 * 33]); o.z = cvt_pk_bf16(s[4 * 33], s[5 * 33]); o.w = cvt_pk_bf16(s[6 * 33], s[7 * 33]);
;         *(u32x4*)(WT + (size_t)(n0 + n) * K + k0 + 8 * c) = o; }
;     LDS_FENCE();
; }
; __global__ void __launch_bounds__(512, 2) fwd_kernel(Params p) {
;     ...
;         int base = 0;
;         for (int j = 0; j < 2; ++j) transpose_job(w_in_moba + (size_t)j * D * NMOBA, NMOBA, D, NMOBA, g_mix + (2 * j + 1) * D, WT + wt_in(2 * j + 1), scr, base, gwave, gwaves, lane);
;         for (int i = 0; i < 4; ++i) transpose_job(w_mem_kv + (size_t)i * D * 512, 512, D, 512, g_mem + i * D, WT + WT_MEM + (size_t)i * 512 * D, scr, base, gwave, gwaves, lane);
;         for (int i = 0; i < 4; ++i) transpose_job(w_out + (size_t)i * D * D, D, D, D, nullptr, WT + WT_OUT + (size_t)i * D * D, scr, base, gwave, gwaves, lane);
;         for (int i = 0; i < 4; ++i) transpose_job(w_ff1 + (size_t)i * D * DFF, DFF, D, DFF, g_mlp + i * D, WT + WT_FF1 + (size_t)i * DFF * D, scr, base, gwave, gwaves, lane);
;         for (int i = 0; i < 4; ++i) transpose_job(w_ff2 + (size_t)i * DFF * D, D, DFF, D, nullptr, WT + WT_FF2 + (size_t)i * D * DFF, scr, base, gwave, gwaves, lane);
;         for (int j = 0; j < 2; ++j) transpose_job(w_in_pool + (size_t)j * D * D + 768, D, D, 256, g_mix + (2 * j) * D, WT + wt_in(2 * j) + (size_t)768 * D, scr, base, gwave, gwaves, lane);
.LBB0_7:
	s_or_b64 exec, exec, s[2:3]
	v_readlane_b32 s4, v252, 0
	s_lshr_b32 s33, s10, 6
	s_lshl_b32 s54, s4, 3
	s_lshl_b32 s70, s68, 9
	s_add_i32 s10, s33, s54
	s_lshl_b32 s30, s68, 3
	s_load_dwordx16 s[12:27], s[0:1], 0x0
	s_load_dwordx16 s[76:91], s[0:1], 0x40
	s_add_u32 s0, s64, 0xa368000
	s_addc_u32 s1, s65, 0
	v_writelane_b32 v252, s0, 4
	s_cmp_lt_i32 s66, 1
	v_and_b32_e32 v148, 63, v204
	v_writelane_b32 v252, s1, 5
	s_cselect_b64 s[0:1], -1, 0
	s_cmp_gt_i32 s67, 0
	s_cselect_b64 s[2:3], -1, 0
	s_and_b64 s[0:1], s[0:1], s[2:3]
	s_andn2_b64 vcc, exec, s[0:1]
	v_lshl_add_u32 v136, s4, 9, v204
	s_cbranch_vccnz .LBB0_320
	s_waitcnt lgkmcnt(0)
	v_lshrrev_b32_e32 v160, 4, v148
	v_and_b32_e32 v161, 15, v148
	v_lshlrev_b32_e32 v161, 4, v161
	v_and_b32_e32 v163, 7, v148
	v_lshlrev_b32_e32 v165, 5, v163
	v_lshrrev_b32_e32 v164, 3, v148
	s_mul_i32 s40, s33, 0x4100
	s_movk_i32 s41, 0x104
	v_mad_u32_u24 v157, v160, s41, v161
	v_add_u32_e32 v157, s40, v157
	s_movk_i32 s41, 0x820
	v_lshlrev_b32_e32 v158, 2, v164
	v_mad_u32_u24 v158, v163, s41, v158
	v_add_u32_e32 v158, s40, v158
	v_lshlrev_b32_e32 v163, 4, v163
	s_mov_b32 s34, s10
.Lft_loop:
	s_cmp_ge_u32 s34, 0x2b80
	s_cbranch_scc1 .Lft_done
	s_cmp_lt_u32 s34, 0x500
	s_cbranch_scc1 .Lft_j1
	s_cmp_lt_u32 s34, 0x700
	s_cbranch_scc1 .Lft_j2
	s_cmp_lt_u32 s34, 0xb00
	s_cbranch_scc1 .Lft_j3
	s_cmp_lt_u32 s34, 0x1b00
	s_cbranch_scc1 .Lft_j4
	s_cmp_lt_u32 s34, 0x2b00
	s_cbranch_scc1 .Lft_j5
	s_branch .Lft_j6
.Lft_j1:
	s_sub_u32 s35, s34, 0x0
	s_cmp_ge_u32 s35, 0x280
	s_cselect_b32 s36, 1, 0
	s_mul_i32 s40, s36, 0x280
	s_sub_u32 s37, s35, s40
	s_mul_i32 s38, s37, 0x667
	s_lshr_b32 s38, s38, 16
	s_mul_i32 s40, s38, 40
	s_sub_u32 s39, s37, s40
	s_mul_i32 s40, s36, 0xa00000
	s_mul_i32 s41, s38, 0xa0000
	s_add_u32 s40, s40, s41
	s_lshl_b32 s41, s39, 8
	s_add_u32 s40, s40, s41
	s_add_u32 s42, s76, s40
	s_addc_u32 s43, s77, 0
	s_mul_i32 s40, s36, 0x700000
	s_mul_i32 s41, s39, 0x20000
	s_add_u32 s40, s40, s41
	s_lshl_b32 s41, s38, 7
	s_add_u32 s40, s40, s41
	s_add_u32 s40, s40, 0x200000
	s_add_u32 s44, s64, s40
	s_addc_u32 s45, s65, 0
	s_mul_i32 s40, s36, 0x2000
	s_lshl_b32 s41, s38, 8
	s_add_u32 s40, s40, s41
	s_add_u32 s40, s40, 0x1000
	s_add_u32 s46, s16, s40
	s_addc_u32 s47, s17, 0
	s_mov_b32 s55, 1
	s_movk_i32 s48, 0x2800
	s_mov_b32 s49, 0xa000
	s_movk_i32 s50, 0x800
	s_mov_b32 s51, 0x4000
	s_branch .Lft_body
.Lft_j2:
	s_sub_u32 s35, s34, 0x500
	s_lshr_b32 s36, s35, 7
	s_and_b32 s37, s35, 0x7f
	s_lshr_b32 s38, s37, 3
	s_and_b32 s39, s37, 0x7
	s_mul_i32 s40, s36, 0x200000
	s_mul_i32 s41, s38, 0x20000
	s_add_u32 s40, s40, s41
	s_lshl_b32 s41, s39, 8
	s_add_u32 s40, s40, s41
	s_add_u32 s42, s82, s40
	s_addc_u32 s43, s83, 0
	s_mul_i32 s40, s36, 0x100000
	s_mul_i32 s41, s39, 0x20000
	s_add_u32 s40, s40, s41
	s_lshl_b32 s41, s38, 7
	s_add_u32 s40, s40, s41
	s_add_u32 s40, s40, 0x5600000
	s_add_u32 s44, s64, s40
	s_addc_u32 s45, s65, 0
	s_mul_i32 s40, s36, 0x1000
	s_lshl_b32 s41, s38, 8
	s_add_u32 s40, s40, s41
	s_add_u32 s46, s18, s40
	s_addc_u32 s47, s19, 0
	s_mov_b32 s55, 1
	s_movk_i32 s48, 0x800
	s_mov_b32 s49, 0x2000
	s_movk_i32 s50, 0x800
	s_mov_b32 s51, 0x4000
	s_branch .Lft_body
.Lft_j3:
	s_sub_u32 s35, s34, 0x700
	s_lshr_b32 s36, s35, 8
	s_and_b32 s37, s35, 0xff
	s_lshr_b32 s38, s37, 4
	s_and_b32 s39, s37, 0xf
	s_mul_i32 s40, s36, 0x400000
	s_mul_i32 s41, s38, 0x40000
	s_add_u32 s40, s40, s41
	s_lshl_b32 s41, s39, 8
	s_add_u32 s40, s40, s41
	s_add_u32 s42, s88, s40
	s_addc_u32 s43, s89, 0
	s_mul_i32 s40, s36, 0x200000
	s_mul_i32 s41, s39, 0x20000
	s_add_u32 s40, s40, s41
	s_lshl_b32 s41, s38, 7
	s_add_u32 s40, s40, s41
	s_add_u32 s40, s40, 0xe00000
	s_add_u32 s44, s64, s40
	s_addc_u32 s45, s65, 0
	s_mov_b32 s55, 0
	s_movk_i32 s48, 0x1000
	s_mov_b32 s49, 0x4000
	s_movk_i32 s50, 0x800
	s_mov_b32 s51, 0x4000
	s_branch .Lft_body
.Lft_j4:
	s_sub_u32 s35, s34, 0xb00
	s_lshr_b32 s36, s35, 10
	s_and_b32 s37, s35, 0x3ff
	s_lshr_b32 s38, s37, 6
	s_and_b32 s39, s37, 0x3f
	s_mul_i32 s40, s36, 0x1000000
	s_mul_i32 s41, s38, 0x100000
	s_add_u32 s40, s40, s41
	s_lshl_b32 s41, s39, 8
	s_add_u32 s40, s40, s41
	s_add_u32 s42, s90, s40
	s_addc_u32 s43, s91, 0
	s_mul_i32 s40, s36, 0x800000
	s_mul_i32 s41, s39, 0x20000
	s_add_u32 s40, s40, s41
	s_lshl_b32 s41, s38, 7
	s_add_u32 s40, s40, s41
	s_add_u32 s40, s40, 0x1600000
	s_add_u32 s44, s64, s40
	s_addc_u32 s45, s65, 0
	s_mul_i32 s40, s36, 0x1000
	s_lshl_b32 s41, s38, 8
	s_add_u32 s40, s40, s41
	s_add_u32 s46, s20, s40
	s_addc_u32 s47, s21, 0
	s_mov_b32 s55, 1
	s_movk_i32 s48, 0x4000
	s_mov_b32 s49, 0x10000
	s_movk_i32 s50, 0x800
	s_mov_b32 s51, 0x4000
	s_branch .Lft_body
.Lft_j5:
	s_sub_u32 s35, s34, 0x1b00
	s_lshr_b32 s36, s35, 10
	s_and_b32 s37, s35, 0x3ff
	s_lshr_b32 s38, s37, 4
	s_and_b32 s39, s37, 0xf
	s_mul_i32 s40, s36, 0x1000000
	s_mul_i32 s41, s38, 0x40000
	s_add_u32 s40, s40, s41
	s_lshl_b32 s41, s39, 8
	s_add_u32 s40, s40, s41
	s_add_u32 s42, s60, s40
	s_addc_u32 s43, s61, 0
	s_mul_i32 s40, s36, 0x800000
	s_mul_i32 s41, s39, 0x80000
	s_add_u32 s40, s40, s41
	s_lshl_b32 s41, s38, 7
	s_add_u32 s40, s40, s41
	s_add_u32 s40, s40, 0x3600000
	s_add_u32 s44, s64, s40
	s_addc_u32 s45, s65, 0
	s_mov_b32 s55, 0
	s_movk_i32 s48, 0x1000
	s_mov_b32 s49, 0x4000
	s_movk_i32 s50, 0x2000
	s_mov_b32 s51, 0x10000
	s_branch .Lft_body
; __device__ __forceinline__ unsigned cvt_pk_bf16(float lo, float hi) { unsigned r; asm volatile("v_cvt_pk_bf16_f32 %0, %1, %2" : "=v"(r) : "v"(lo), "v"(hi)); return r; }
; #define LDS_FENCE() asm volatile("s_waitcnt lgkmcnt(0)" ::: "memory")
; __device__ __forceinline__ void transpose_item(const float* __restrict__ W, int ldw, int K, int N, const float* __restrict__ g, bf16_t* __restrict__ WT, float* scr, int item, int lane) {
;     const int nblk = N / 32, kb = item / nblk, nb = item - kb * nblk, k0 = 64 * kb, n0 = 32 * nb;
; #pragma unroll 8
;     for (int i = 0; i < 32; ++i) { const int kk = 2 * i + (lane >> 5); float v = W[(size_t)(k0 + kk) * ldw + n0 + (lane & 31)]; if (g) v *= g[k0 + kk]; scr[kk * 33 + (lane & 31)] = v; }
;     LDS_FENCE();
;     const int c = lane & 7;
; #pragma unroll
;     for (int j = 0; j < 4; ++j) { const int n = (lane >> 3) + 8 * j; const float* s = scr + (8 * c) * 33 + n;
;         u32x4 o; o.x = cvt_pk_bf16(s[0 * 33], s[1 * 33]); o.y = cvt_pk_bf16(s[2 * 33], s[3 * 33]); o.z = cvt_pk_bf16(s[4 * 33], s[5 * 33]); o.w = cvt_pk_bf16(s[6 * 33], s[7 * 33]);
;         *(u32x4*)(WT + (size_t)(n0 + n) * K + k0 + 8 * c) = o; }
;     LDS_FENCE();
; }
.Lft_j6:
	s_sub_u32 s35, s34, 0x2b00
	s_lshr_b32 s36, s35, 6
	s_and_b32 s37, s35, 0x3f
	s_lshr_b32 s38, s37, 2
	s_and_b32 s39, s37, 0x3
	s_mul_i32 s40, s36, 0x400000
	s_mul_i32 s41, s38, 0x40000
	s_add_u32 s40, s40, s41
	s_lshl_b32 s41, s39, 8
	s_add_u32 s40, s40, s41
	s_add_u32 s40, s40, 0xc00
	s_add_u32 s42, s22, s40
	s_addc_u32 s43, s23, 0
	s_mul_i32 s40, s36, 0x700000
	s_mul_i32 s41, s39, 0x20000
	s_add_u32 s40, s40, s41
	s_lshl_b32 s41, s38, 7
	s_add_u32 s40, s40, s41
	s_add_u32 s40, s40, 0x180000
	s_add_u32 s44, s64, s40
	s_addc_u32 s45, s65, 0
	s_mul_i32 s40, s36, 0x2000
	s_lshl_b32 s41, s38, 8
	s_add_u32 s40, s40, s41
	s_add_u32 s46, s16, s40
	s_addc_u32 s47, s17, 0
	s_mov_b32 s55, 1
	s_movk_i32 s48, 0x1000
	s_mov_b32 s49, 0x4000
	s_movk_i32 s50, 0x800
	s_mov_b32 s51, 0x4000
	s_branch .Lft_body
.Lft_body:
	v_mad_u32_u24 v154, v160, s48, v161
	v_mad_u32_u24 v155, v164, s50, v163
	s_cmp_eq_u32 s55, 0
	s_cbranch_scc1 .Lft_nog
	global_load_dwordx4 v[128:131], v165, s[46:47]
	global_load_dwordx4 v[132:135], v165, s[46:47] offset:16
.Lft_nog:
	global_load_dwordx4 v[64:67], v154, s[42:43]
	v_add_u32_e32 v154, s49, v154
	global_load_dwordx4 v[68:71], v154, s[42:43]
	v_add_u32_e32 v154, s49, v154
	global_load_dwordx4 v[72:75], v154, s[42:43]
	v_add_u32_e32 v154, s49, v154
	global_load_dwordx4 v[76:79], v154, s[42:43]
	v_add_u32_e32 v154, s49, v154
	global_load_dwordx4 v[80:83], v154, s[42:43]
	v_add_u32_e32 v154, s49, v154
	global_load_dwordx4 v[84:87], v154, s[42:43]
	v_add_u32_e32 v154, s49, v154
	global_load_dwordx4 v[88:91], v154, s[42:43]
	v_add_u32_e32 v154, s49, v154
	global_load_dwordx4 v[92:95], v154, s[42:43]
	v_add_u32_e32 v154, s49, v154
	global_load_dwordx4 v[96:99], v154, s[42:43]
	v_add_u32_e32 v154, s49, v154
	global_load_dwordx4 v[100:103], v154, s[42:43]
	v_add_u32_e32 v154, s49, v154
	global_load_dwordx4 v[104:107], v154, s[42:43]
	v_add_u32_e32 v154, s49, v154
	global_load_dwordx4 v[108:111], v154, s[42:43]
	v_add_u32_e32 v154, s49, v154
	global_load_dwordx4 v[112:115], v154, s[42:43]
	v_add_u32_e32 v154, s49, v154
	global_load_dwordx4 v[116:119], v154, s[42:43]
	v_add_u32_e32 v154, s49, v154
	global_load_dwordx4 v[120:123], v154, s[42:43]
	v_add_u32_e32 v154, s49, v154
	global_load_dwordx4 v[124:127], v154, s[42:43]
	s_waitcnt vmcnt(15)
	ds_write_b32 v157, v64
	ds_write_b32 v157, v65 offset:4
	ds_write_b32 v157, v66 offset:8
	ds_write_b32 v157, v67 offset:12
	s_waitcnt vmcnt(14)
	ds_write_b32 v157, v68 offset:1040
	ds_write_b32 v157, v69 offset:1044
	ds_write_b32 v157, v70 offset:1048
	ds_write_b32 v157, v71 offset:1052
	s_waitcnt vmcnt(13)
	ds_write_b32 v157, v72 offset:2080
	ds_write_b32 v157, v73 offset:2084
	ds_write_b32 v157, v74 offset:2088
	ds_write_b32 v157, v75 offset:2092
	s_waitcnt vmcnt(12)
	ds_write_b32 v157, v76 offset:3120
	ds_write_b32 v157, v77 offset:3124
	ds_write_b32 v157, v78 offset:3128
	ds_write_b32 v157, v79 offset:3132
	s_waitcnt vmcnt(11)
	ds_write_b32 v157, v80 offset:4160
	ds_write_b32 v157, v81 offset:4164
	ds_write_b32 v157, v82 offset:4168
	ds_write_b32 v157, v83 offset:4172
	s_waitcnt vmcnt(10)
	ds_write_b32 v157, v84 offset:5200
	ds_write_b32 v157, v85 offset:5204
	ds_write_b32 v157, v86 offset:5208
	ds_write_b32 v157, v87 offset:5212
	s_waitcnt vmcnt(9)
	ds_write_b32 v157, v88 offset:6240
	ds_write_b32 v157, v89 offset:6244
	ds_write_b32 v157, v90 offset:6248
	ds_write_b32 v157, v91 offset:6252
	s_waitcnt vmcnt(8)
	ds_write_b32 v157, v92 offset:7280
	ds_write_b32 v157, v93 offset:7284
	ds_write_b32 v157, v94 offset:7288
	ds_write_b32 v157, v95 offset:7292
	s_waitcnt vmcnt(7)
	ds_write_b32 v157, v96 offset:8320
	ds_write_b32 v157, v97 offset:8324
	ds_write_b32 v157, v98 offset:8328
	ds_write_b32 v157, v99 offset:8332
	s_waitcnt vmcnt(6)
	ds_write_b32 v157, v100 offset:9360
	ds_write_b32 v157, v101 offset:9364
	ds_write_b32 v157, v102 offset:9368
	ds_write_b32 v157, v103 offset:9372
	s_waitcnt vmcnt(5)
	ds_write_b32 v157, v104 offset:10400
	ds_write_b32 v157, v105 offset:10404
	ds_write_b32 v157, v106 offset:10408
	ds_write_b32 v157, v107 offset:10412
	s_waitcnt vmcnt(4)
	ds_write_b32 v157, v108 offset:11440
	ds_write_b32 v157, v109 offset:11444
	ds_write_b32 v157, v110 offset:11448
	ds_write_b32 v157, v111 offset:11452
	s_waitcnt vmcnt(3)
	ds_write_b32 v157, v112 offset:12480
	ds_write_b32 v157, v113 offset:12484
	ds_write_b32 v157, v114 offset:12488
	ds_write_b32 v157, v115 offset:12492
	s_waitcnt vmcnt(2)
	ds_write_b32 v157, v116 offset:13520
	ds_write_b32 v157, v117 offset:13524
	ds_write_b32 v157, v118 offset:13528
	ds_write_b32 v157, v119 offset:13532
	s_waitcnt vmcnt(1)
	ds_write_b32 v157, v120 offset:14560
	ds_write_b32 v157, v121 offset:14564
	ds_write_b32 v157, v122 offset:14568
	ds_write_b32 v157, v123 offset:14572
	s_waitcnt vmcnt(0)
	ds_write_b32 v157, v124 offset:15600
	ds_write_b32 v157, v125 offset:15604
	ds_write_b32 v157, v126 offset:15608
	ds_write_b32 v157, v127 offset:15612
	s_waitcnt lgkmcnt(0)
	ds_read_b32 v137, v158
	ds_read_b32 v138, v158 offset:260
	ds_read_b32 v139, v158 offset:520
	ds_read_b32 v140, v158 offset:780
	ds_read_b32 v141, v158 offset:1040
	ds_read_b32 v142, v158 offset:1300
	ds_read_b32 v143, v158 offset:1560
	ds_read_b32 v144, v158 offset:1820
	v_add_u32_e32 v159, s51, v155
	s_cmp_eq_u32 s55, 0
	s_waitcnt lgkmcnt(0)
	s_cbranch_scc1 .Lft_nomul0
	v_mul_f32_e32 v137, v137, v128
	v_mul_f32_e32 v138, v138, v129
	v_mul_f32_e32 v139, v139, v130
	v_mul_f32_e32 v140, v140, v131
	v_mul_f32_e32 v141, v141, v132
	v_mul_f32_e32 v142, v142, v133
	v_mul_f32_e32 v143, v143, v134
	v_mul_f32_e32 v144, v144, v135
; __device__ __forceinline__ unsigned cvt_pk_bf16(float lo, float hi) { unsigned r; asm volatile("v_cvt_pk_bf16_f32 %0, %1, %2" : "=v"(r) : "v"(lo), "v"(hi)); return r; }
; #define LDS_FENCE() asm volatile("s_waitcnt lgkmcnt(0)" ::: "memory")
; __device__ __forceinline__ void transpose_item(const float* __restrict__ W, int ldw, int K, int N, const float* __restrict__ g, bf16_t* __restrict__ WT, float* scr, int item, int lane) {
;     ...
;     for (int i = 0; i < 32; ++i) { const int kk = 2 * i + (lane >> 5); float v = W[(size_t)(k0 + kk) * ldw + n0 + (lane & 31)]; if (g) v *= g[k0 + kk]; scr[kk * 33 + (lane & 31)] = v; }
;     LDS_FENCE();
;     const int c = lane & 7;
; #pragma unroll
;     for (int j = 0; j < 4; ++j) { const int n = (lane >> 3) + 8 * j; const float* s = scr + (8 * c) * 33 + n;
;         u32x4 o; o.x = cvt_pk_bf16(s[0 * 33], s[1 * 33]); o.y = cvt_pk_bf16(s[2 * 33], s[3 * 33]); o.z = cvt_pk_bf16(s[4 * 33], s[5 * 33]); o.w = cvt_pk_bf16(s[6 * 33], s[7 * 33]);
;         *(u32x4*)(WT + (size_t)(n0 + n) * K + k0 + 8 * c) = o; }
.Lft_nomul0:
	v_cvt_pk_bf16_f32 v150, v137, v138
	v_cvt_pk_bf16_f32 v151, v139, v140
	v_cvt_pk_bf16_f32 v152, v141, v142
	v_cvt_pk_bf16_f32 v153, v143, v144
	global_store_dwordx4 v155, v[150:153], s[44:45]
	ds_read_b32 v137, v158 offset:32
	ds_read_b32 v138, v158 offset:292
	ds_read_b32 v139, v158 offset:552
	ds_read_b32 v140, v158 offset:812
	ds_read_b32 v141, v158 offset:1072
	ds_read_b32 v142, v158 offset:1332
	ds_read_b32 v143, v158 offset:1592
	ds_read_b32 v144, v158 offset:1852
	v_add_u32_e32 v155, s51, v159
	s_cmp_eq_u32 s55, 0
	s_waitcnt lgkmcnt(0)
	s_cbranch_scc1 .Lft_nomul1
	v_mul_f32_e32 v137, v137, v128
	v_mul_f32_e32 v138, v138, v129
	v_mul_f32_e32 v139, v139, v130
	v_mul_f32_e32 v140, v140, v131
	v_mul_f32_e32 v141, v141, v132
	v_mul_f32_e32 v142, v142, v133
	v_mul_f32_e32 v143, v143, v134
	v_mul_f32_e32 v144, v144, v135
.Lft_nomul1:
	v_cvt_pk_bf16_f32 v150, v137, v138
	v_cvt_pk_bf16_f32 v151, v139, v140
	v_cvt_pk_bf16_f32 v152, v141, v142
	v_cvt_pk_bf16_f32 v153, v143, v144
	global_store_dwordx4 v159, v[150:153], s[44:45]
	ds_read_b32 v137, v158 offset:64
	ds_read_b32 v138, v158 offset:324
	ds_read_b32 v139, v158 offset:584
	ds_read_b32 v140, v158 offset:844
	ds_read_b32 v141, v158 offset:1104
	ds_read_b32 v142, v158 offset:1364
	ds_read_b32 v143, v158 offset:1624
	ds_read_b32 v144, v158 offset:1884
	v_add_u32_e32 v159, s51, v155
	s_cmp_eq_u32 s55, 0
	s_waitcnt lgkmcnt(0)
	s_cbranch_scc1 .Lft_nomul2
	v_mul_f32_e32 v137, v137, v128
	v_mul_f32_e32 v138, v138, v129
	v_mul_f32_e32 v139, v139, v130
	v_mul_f32_e32 v140, v140, v131
	v_mul_f32_e32 v141, v141, v132
	v_mul_f32_e32 v142, v142, v133
	v_mul_f32_e32 v143, v143, v134
	v_mul_f32_e32 v144, v144, v135
.Lft_nomul2:
	v_cvt_pk_bf16_f32 v150, v137, v138
	v_cvt_pk_bf16_f32 v151, v139, v140
	v_cvt_pk_bf16_f32 v152, v141, v142
	v_cvt_pk_bf16_f32 v153, v143, v144
	global_store_dwordx4 v155, v[150:153], s[44:45]
	ds_read_b32 v137, v158 offset:96
	ds_read_b32 v138, v158 offset:356
	ds_read_b32 v139, v158 offset:616
	ds_read_b32 v140, v158 offset:876
	ds_read_b32 v141, v158 offset:1136
	ds_read_b32 v142, v158 offset:1396
	ds_read_b32 v143, v158 offset:1656
	ds_read_b32 v144, v158 offset:1916
	v_add_u32_e32 v155, s51, v159
	s_cmp_eq_u32 s55, 0
	s_waitcnt lgkmcnt(0)
	s_cbranch_scc1 .Lft_nomul3
	v_mul_f32_e32 v137, v137, v128
	v_mul_f32_e32 v138, v138, v129
	v_mul_f32_e32 v139, v139, v130
	v_mul_f32_e32 v140, v140, v131
	v_mul_f32_e32 v141, v141, v132
	v_mul_f32_e32 v142, v142, v133
	v_mul_f32_e32 v143, v143, v134
	v_mul_f32_e32 v144, v144, v135
.Lft_nomul3:
	v_cvt_pk_bf16_f32 v150, v137, v138
	v_cvt_pk_bf16_f32 v151, v139, v140
	v_cvt_pk_bf16_f32 v152, v141, v142
	v_cvt_pk_bf16_f32 v153, v143, v144
	global_store_dwordx4 v159, v[150:153], s[44:45]
	ds_read_b32 v137, v158 offset:128
	ds_read_b32 v138, v158 offset:388
	ds_read_b32 v139, v158 offset:648
	ds_read_b32 v140, v158 offset:908
	ds_read_b32 v141, v158 offset:1168
	ds_read_b32 v142, v158 offset:1428
	ds_read_b32 v143, v158 offset:1688
	ds_read_b32 v144, v158 offset:1948
	v_add_u32_e32 v159, s51, v155
	s_cmp_eq_u32 s55, 0
	s_waitcnt lgkmcnt(0)
	s_cbranch_scc1 .Lft_nomul4
	v_mul_f32_e32 v137, v137, v128
	v_mul_f32_e32 v138, v138, v129
	v_mul_f32_e32 v139, v139, v130
	v_mul_f32_e32 v140, v140, v131
	v_mul_f32_e32 v141, v141, v132
	v_mul_f32_e32 v142, v142, v133
	v_mul_f32_e32 v143, v143, v134
	v_mul_f32_e32 v144, v144, v135
.Lft_nomul4:
	v_cvt_pk_bf16_f32 v150, v137, v138
	v_cvt_pk_bf16_f32 v151, v139, v140
	v_cvt_pk_bf16_f32 v152, v141, v142
	v_cvt_pk_bf16_f32 v153, v143, v144
	global_store_dwordx4 v155, v[150:153], s[44:45]
	ds_read_b32 v137, v158 offset:160
	ds_read_b32 v138, v158 offset:420
	ds_read_b32 v139, v158 offset:680
	ds_read_b32 v140, v158 offset:940
	ds_read_b32 v141, v158 offset:1200
	ds_read_b32 v142, v158 offset:1460
	ds_read_b32 v143, v158 offset:1720
	ds_read_b32 v144, v158 offset:1980
	v_add_u32_e32 v155, s51, v159
	s_cmp_eq_u32 s55, 0
	s_waitcnt lgkmcnt(0)
	s_cbranch_scc1 .Lft_nomul5
	v_mul_f32_e32 v137, v137, v128
	v_mul_f32_e32 v138, v138, v129
	v_mul_f32_e32 v139, v139, v130
	v_mul_f32_e32 v140, v140, v131
	v_mul_f32_e32 v141, v141, v132
	v_mul_f32_e32 v142, v142, v133
	v_mul_f32_e32 v143, v143, v134
	v_mul_f32_e32 v144, v144, v135
; __device__ __forceinline__ unsigned cvt_pk_bf16(float lo, float hi) { unsigned r; asm volatile("v_cvt_pk_bf16_f32 %0, %1, %2" : "=v"(r) : "v"(lo), "v"(hi)); return r; }
; #define LDS_FENCE() asm volatile("s_waitcnt lgkmcnt(0)" ::: "memory")
; __device__ __forceinline__ void transpose_item(const float* __restrict__ W, int ldw, int K, int N, const float* __restrict__ g, bf16_t* __restrict__ WT, float* scr, int item, int lane) {
;     const int nblk = N / 32, kb = item / nblk, nb = item - kb * nblk, k0 = 64 * kb, n0 = 32 * nb;
; #pragma unroll 8
;     for (int i = 0; i < 32; ++i) { const int kk = 2 * i + (lane >> 5); float v = W[(size_t)(k0 + kk) * ldw + n0 + (lane & 31)]; if (g) v *= g[k0 + kk]; scr[kk * 33 + (lane & 31)] = v; }
;     LDS_FENCE();
;     const int c = lane & 7;
; #pragma unroll
;     for (int j = 0; j < 4; ++j) { const int n = (lane >> 3) + 8 * j; const float* s = scr + (8 * c) * 33 + n;
;         u32x4 o; o.x = cvt_pk_bf16(s[0 * 33], s[1 * 33]); o.y = cvt_pk_bf16(s[2 * 33], s[3 * 33]); o.z = cvt_pk_bf16(s[4 * 33], s[5 * 33]); o.w = cvt_pk_bf16(s[6 * 33], s[7 * 33]);
;         *(u32x4*)(WT + (size_t)(n0 + n) * K + k0 + 8 * c) = o; }
;     LDS_FENCE();
; }
; __device__ __forceinline__ void transpose_job(const float* W, int ldw, int K, int N, const float* g, bf16_t* WT, float* scr, int& base, int gwave, int gwaves, int lane) {
;     const int nitems = (K / 64) * (N / 32);
;     int start = (gwave - (base % gwaves) + gwaves) % gwaves;
;     int it = start;
;     for (; it + gwaves < nitems; it += 2 * gwaves) transpose_item2(W, ldw, K, N, g, WT, scr, it, it + gwaves, lane);
;     if (it < nitems) transpose_item(W, ldw, K, N, g, WT, scr, it, lane);
;     base += nitems;
.Lft_nomul5:
	v_cvt_pk_bf16_f32 v150, v137, v138
	v_cvt_pk_bf16_f32 v151, v139, v140
	v_cvt_pk_bf16_f32 v152, v141, v142
	v_cvt_pk_bf16_f32 v153, v143, v144
	global_store_dwordx4 v159, v[150:153], s[44:45]
	ds_read_b32 v137, v158 offset:192
	ds_read_b32 v138, v158 offset:452
	ds_read_b32 v139, v158 offset:712
	ds_read_b32 v140, v158 offset:972
	ds_read_b32 v141, v158 offset:1232
	ds_read_b32 v142, v158 offset:1492
	ds_read_b32 v143, v158 offset:1752
	ds_read_b32 v144, v158 offset:2012
	v_add_u32_e32 v159, s51, v155
	s_cmp_eq_u32 s55, 0
	s_waitcnt lgkmcnt(0)
	s_cbranch_scc1 .Lft_nomul6
	v_mul_f32_e32 v137, v137, v128
	v_mul_f32_e32 v138, v138, v129
	v_mul_f32_e32 v139, v139, v130
	v_mul_f32_e32 v140, v140, v131
	v_mul_f32_e32 v141, v141, v132
	v_mul_f32_e32 v142, v142, v133
	v_mul_f32_e32 v143, v143, v134
	v_mul_f32_e32 v144, v144, v135
.Lft_nomul6:
	v_cvt_pk_bf16_f32 v150, v137, v138
	v_cvt_pk_bf16_f32 v151, v139, v140
	v_cvt_pk_bf16_f32 v152, v141, v142
	v_cvt_pk_bf16_f32 v153, v143, v144
	global_store_dwordx4 v155, v[150:153], s[44:45]
	ds_read_b32 v137, v158 offset:224
	ds_read_b32 v138, v158 offset:484
	ds_read_b32 v139, v158 offset:744
	ds_read_b32 v140, v158 offset:1004
	ds_read_b32 v141, v158 offset:1264
	ds_read_b32 v142, v158 offset:1524
	ds_read_b32 v143, v158 offset:1784
	ds_read_b32 v144, v158 offset:2044
	s_cmp_eq_u32 s55, 0
	s_waitcnt lgkmcnt(0)
	s_cbranch_scc1 .Lft_nomul7
	v_mul_f32_e32 v137, v137, v128
	v_mul_f32_e32 v138, v138, v129
	v_mul_f32_e32 v139, v139, v130
	v_mul_f32_e32 v140, v140, v131
	v_mul_f32_e32 v141, v141, v132
	v_mul_f32_e32 v142, v142, v133
	v_mul_f32_e32 v143, v143, v134
	v_mul_f32_e32 v144, v144, v135
.Lft_nomul7:
	v_cvt_pk_bf16_f32 v150, v137, v138
	v_cvt_pk_bf16_f32 v151, v139, v140
	v_cvt_pk_bf16_f32 v152, v141, v142
	v_cvt_pk_bf16_f32 v153, v143, v144
	global_store_dwordx4 v159, v[150:153], s[44:45]
	s_add_u32 s34, s34, s30
	s_branch .Lft_loop
.Lft_done:
	s_waitcnt vmcnt(0) lgkmcnt(0)
	v_lshlrev_b32_e32 v0, 3, v204
	s_mul_i32 s42, s33, 0x2100
	v_lshrrev_b32_e32 v179, 3, v148
	v_and_b32_e32 v10, 56, v0
	s_add_i32 s0, s42, 0
	v_mul_u32_u24_e32 v0, 0x84, v10
	v_lshlrev_b32_e32 v1, 2, v179
	s_abs_i32 s31, s30
	v_add3_u32 v180, s0, v0, v1
	v_cvt_f32_u32_e32 v0, s31
	v_and_b32_e32 v8, 31, v204
	v_lshl_add_u32 v6, v8, 2, s0
	s_sub_i32 s2, 0, s31
	v_rcp_iflag_f32_e32 v0, v0
	v_lshrrev_b32_e32 v4, 5, v148
	s_movk_i32 s43, 0x84
	v_mad_u32_u24 v181, v4, s43, v6
	v_mul_f32_e32 v0, 0x4f7ffffe, v0
	v_cvt_u32_f32_e32 v0, v0
	s_lshl_b32 s46, s68, 8
	s_mov_b32 s1, 0
	s_add_i32 s11, s10, s30
	v_readfirstlane_b32 s0, v0
	s_mul_i32 s2, s2, s0
	s_mul_hi_u32 s2, s0, s2
	v_or_b32_e32 v137, 2, v4
	v_or_b32_e32 v149, 4, v4
	v_or_b32_e32 v150, 6, v4
	v_or_b32_e32 v151, 8, v4
	v_or_b32_e32 v152, 10, v4
	v_or_b32_e32 v153, 12, v4
	v_or_b32_e32 v154, 14, v4
	v_or_b32_e32 v155, 16, v4
	v_or_b32_e32 v156, 18, v4
	v_or_b32_e32 v157, 20, v4
	v_or_b32_e32 v158, 22, v4
	v_or_b32_e32 v159, 24, v4
	v_or_b32_e32 v160, 26, v4
	v_or_b32_e32 v161, 28, v4
	v_or_b32_e32 v162, 30, v4
	v_or_b32_e32 v163, 32, v4
	v_or_b32_e32 v164, 34, v4
	v_or_b32_e32 v165, 36, v4
	v_or_b32_e32 v166, 38, v4
	v_or_b32_e32 v167, 40, v4
	v_or_b32_e32 v168, 42, v4
	v_or_b32_e32 v169, 44, v4
	v_or_b32_e32 v170, 46, v4
	v_or_b32_e32 v171, 48, v4
	v_or_b32_e32 v172, 50, v4
	v_or_b32_e32 v173, 52, v4
	v_or_b32_e32 v174, 54, v4
	v_or_b32_e32 v175, 56, v4
	v_or_b32_e32 v176, 58, v4
	v_or_b32_e32 v177, 60, v4
	v_or_b32_e32 v178, 62, v4
	v_add_u32_e32 v182, 0x108, v181
	v_add_u32_e32 v183, 0x210, v181
	v_add_u32_e32 v184, 0x318, v181
	v_add_u32_e32 v185, 0x420, v181
	v_add_u32_e32 v186, 0x528, v181
	v_add_u32_e32 v187, 0x630, v181
	v_add_u32_e32 v188, 0x738, v181
	v_add_u32_e32 v189, 0x840, v181
	v_add_u32_e32 v190, 0x948, v181
	v_add_u32_e32 v191, 0xa50, v181
	v_add_u32_e32 v192, 0xb58, v181
	v_add_u32_e32 v193, 0xc60, v181
	v_add_u32_e32 v194, 0xd68, v181
	v_add_u32_e32 v195, 0xe70, v181
	v_add_u32_e32 v196, 0xf78, v181
	v_add_u32_e32 v197, 0x1080, v181
	s_lshl_b32 s44, s68, 4
	s_add_i32 s45, s0, s2
	s_mov_b64 s[8:9], -1
	s_movk_i32 s47, 0x2800
	s_mov_b32 s4, 0
	s_mov_b32 s48, 0
	v_add_u32_e32 v198, 0x1188, v181
	v_add_u32_e32 v199, 0x1290, v181
	v_add_u32_e32 v200, 0x1398, v181
	v_add_u32_e32 v201, 0x14a0, v181
	v_add_u32_e32 v202, 0x15a8, v181
	v_add_u32_e32 v203, 0x16b0, v181
	v_add_u32_e32 v205, 0x17b8, v181
	v_add_u32_e32 v206, 0x18c0, v181
	v_add_u32_e32 v207, 0x19c8, v181
	v_add_u32_e32 v208, 0x1ad0, v181
	v_add_u32_e32 v209, 0x1bd8, v181
	v_add_u32_e32 v210, 0x1ce0, v181
	v_add_u32_e32 v211, 0x1de8, v181
	v_add_u32_e32 v212, 0x1ef0, v181
	v_add_u32_e32 v213, 0x1ff8, v181
	v_or_b32_e32 v214, 8, v179
	v_or_b32_e32 v215, 16, v179
	v_or_b32_e32 v216, 24, v179
	v_or_b32_e32 v217, s46, v179
	v_mov_b32_e32 v13, 0
	v_mov_b32_e32 v5, v4
	s_branch .LBB0_10

; __device__ __forceinline__ void transpose_job(const float* W, int ldw, int K, int N, const float* g, bf16_t* WT, float* scr, int& base, int gwave, int gwaves, int lane) {
;     const int nitems = (K / 64) * (N / 32);
;     int start = (gwave - (base % gwaves) + gwaves) % gwaves;
;     int it = start;
;     for (; it + gwaves < nitems; it += 2 * gwaves) transpose_item2(W, ldw, K, N, g, WT, scr, it, it + gwaves, lane);
;     if (it < nitems) transpose_item(W, ldw, K, N, g, WT, scr, it, lane);
;     base += nitems;
; __global__ void __launch_bounds__(512, 2) fwd_kernel(Params p) {
;     ...
;         for (int j = 0; j < 2; ++j) transpose_job(w_in_moba + (size_t)j * D * NMOBA, NMOBA, D, NMOBA, g_mix + (2 * j + 1) * D, WT + wt_in(2 * j + 1), scr, base, gwave, gwaves, lane);
.LBB0_10:
	s_mul_i32 s0, s4, 0x280000
	s_lshl_b64 s[2:3], s[0:1], 2
	s_waitcnt lgkmcnt(0)
	s_add_u32 s34, s76, s2
	s_addc_u32 s35, s77, s3
	s_lshl_b32 s0, s4, 11
	s_lshl_b64 s[2:3], s[0:1], 2
	s_add_u32 s0, s16, s2
	s_addc_u32 s2, s17, s3
	s_add_u32 s6, s0, 0x1000
	s_mul_i32 s0, s4, 0x380000
	s_addc_u32 s7, s2, 0
	s_lshl_b64 s[2:3], s[0:1], 1
	s_add_u32 s0, s64, s2
	s_addc_u32 s2, s65, s3
	s_add_u32 s4, s0, 0x200000
	s_mul_hi_u32 s0, s48, s45
	s_mul_i32 s0, s0, s31
	s_addc_u32 s5, s2, 0
	s_sub_i32 s0, s48, s0
	s_sub_i32 s2, s0, s31
	s_cmp_ge_u32 s0, s31
	s_cselect_b32 s0, s2, s0
	s_sub_i32 s2, s0, s31
	s_cmp_ge_u32 s0, s31
	s_cselect_b32 s0, s2, s0
	s_sub_i32 s0, s11, s0
	s_ashr_i32 s2, s0, 31
	s_abs_i32 s0, s0
	s_mul_hi_u32 s3, s0, s45
	s_mul_i32 s3, s3, s31
	s_sub_i32 s0, s0, s3
	s_sub_i32 s3, s0, s31
	s_cmp_ge_u32 s0, s31
	s_cselect_b32 s0, s3, s0
	s_sub_i32 s3, s0, s31
	s_cmp_ge_u32 s0, s31
	s_cselect_b32 s0, s3, s0
	s_xor_b32 s3, s0, s2
	s_sub_i32 s0, s3, s2
	s_add_i32 s36, s0, s30
	s_cmpk_gt_i32 s36, 0x4ff
	s_branch .LBB0_13
	v_lshlrev_b32_e32 v12, 2, v8
	v_lshl_add_u64 v[14:15], s[34:35], 0, v[12:13]
	v_lshlrev_b32_e32 v12, 1, v10
	s_lshl_b32 s3, s3, 5
	s_lshl_b32 s2, s2, 5
	v_lshl_add_u64 v[16:17], s[4:5], 0, v[12:13]
	s_sub_i32 s2, s3, s2

; __device__ __forceinline__ void transpose_job(const float* W, int ldw, int K, int N, const float* g, bf16_t* WT, float* scr, int& base, int gwave, int gwaves, int lane) {
;     const int nitems = (K / 64) * (N / 32);
;     int start = (gwave - (base % gwaves) + gwaves) % gwaves;
;     int it = start;
;     for (; it + gwaves < nitems; it += 2 * gwaves) transpose_item2(W, ldw, K, N, g, WT, scr, it, it + gwaves, lane);
;     if (it < nitems) transpose_item(W, ldw, K, N, g, WT, scr, it, lane);
;     base += nitems;
; __global__ void __launch_bounds__(512, 2) fwd_kernel(Params p) {
;     ...
;         for (int j = 0; j < 2; ++j) transpose_job(w_in_moba + (size_t)j * D * NMOBA, NMOBA, D, NMOBA, g_mix + (2 * j + 1) * D, WT + wt_in(2 * j + 1), scr, base, gwave, gwaves, lane);
.LBB0_13:
	s_xor_b64 s[2:3], s[8:9], -1
	s_cmpk_gt_i32 s0, 0x4ff
	s_branch .LBB0_9
	s_mul_hi_i32 s8, s0, 0x66666667
	s_lshr_b32 s9, s8, 31
	s_ashr_i32 s8, s8, 5
	s_add_i32 s8, s8, s9
	s_mul_i32 s9, s8, 0xffffffb0
	s_add_i32 s9, s9, s0
	s_lshl_b32 s36, s8, 6
	s_lshl_b32 s8, s9, 5
	s_ashr_i32 s9, s8, 31
	s_lshl_b64 s[38:39], s[8:9], 2
	s_add_u32 s34, s34, s38
	s_addc_u32 s35, s35, s39
	v_lshlrev_b32_e32 v12, 2, v8
	v_lshl_add_u64 v[0:1], s[34:35], 0, v[12:13]
	v_or_b32_e32 v3, s36, v5
	v_or_b32_e32 v2, s36, v4
	s_mov_b32 s0, 1
	s_mov_b32 s9, 0
	s_mov_b32 s34, 32

; __device__ __forceinline__ void transpose_job(const float* W, int ldw, int K, int N, const float* g, bf16_t* WT, float* scr, int& base, int gwave, int gwaves, int lane) {
;     const int nitems = (K / 64) * (N / 32);
;     int start = (gwave - (base % gwaves) + gwaves) % gwaves;
;     int it = start;
;     for (; it + gwaves < nitems; it += 2 * gwaves) transpose_item2(W, ldw, K, N, g, WT, scr, it, it + gwaves, lane);
;     if (it < nitems) transpose_item(W, ldw, K, N, g, WT, scr, it, lane);
;     base += nitems;
; __global__ void __launch_bounds__(512, 2) fwd_kernel(Params p) {
;     ...
;         for (int i = 0; i < 4; ++i) transpose_job(w_mem_kv + (size_t)i * D * 512, 512, D, 512, g_mem + i * D, WT + WT_MEM + (size_t)i * 512 * D, scr, base, gwave, gwaves, lane);
.LBB0_20:
	s_lshl_b64 s[0:1], s[6:7], 21
	s_add_u32 s38, s82, s0
	s_addc_u32 s39, s83, s1
	s_lshl_b32 s0, s6, 10
	s_mov_b32 s1, s7
	s_lshl_b64 s[0:1], s[0:1], 2
	s_add_u32 s36, s18, s0
	s_addc_u32 s37, s19, s1
	s_lshl_b64 s[0:1], s[6:7], 20
	s_add_u32 s34, s47, s0
	s_mul_hi_u32 s0, s49, s45
	s_mul_i32 s0, s0, s31
	s_addc_u32 s35, s48, s1
	s_sub_i32 s0, s49, s0
	s_sub_i32 s1, s0, s31
	s_cmp_ge_u32 s0, s31
	s_cselect_b32 s0, s1, s0
	s_sub_i32 s1, s0, s31
	s_cmp_ge_u32 s0, s31
	s_cselect_b32 s0, s1, s0
	s_sub_i32 s1, s11, s0
	s_ashr_i32 s0, s1, 31
	s_abs_i32 s1, s1
	s_mul_hi_u32 s2, s1, s45
	s_mul_i32 s2, s2, s31
	s_sub_i32 s1, s1, s2
	s_sub_i32 s2, s1, s31
	s_cmp_ge_u32 s1, s31
	s_cselect_b32 s1, s2, s1
	s_sub_i32 s2, s1, s31
	s_cmp_ge_u32 s1, s31
	s_cselect_b32 s1, s2, s1
	s_xor_b32 s1, s1, s0
	s_sub_i32 s50, s1, s0
	s_add_i32 s2, s50, s30
	s_cmpk_gt_i32 s2, 0xff
	s_branch .LBB0_55
	v_mov_b32_e32 v9, v1
	s_lshl_b32 s1, s1, 5
	s_lshl_b32 s0, s0, 5
	v_lshl_add_u64 v[10:11], s[38:39], 0, v[0:1]
	v_lshl_add_u64 v[12:13], s[34:35], 0, v[8:9]
	s_sub_i32 s51, s1, s0
	s_branch .LBB0_24

; __device__ __forceinline__ void transpose_job(const float* W, int ldw, int K, int N, const float* g, bf16_t* WT, float* scr, int& base, int gwave, int gwaves, int lane) {
;     const int nitems = (K / 64) * (N / 32);
;     int start = (gwave - (base % gwaves) + gwaves) % gwaves;
;     int it = start;
;     for (; it + gwaves < nitems; it += 2 * gwaves) transpose_item2(W, ldw, K, N, g, WT, scr, it, it + gwaves, lane);
;     if (it < nitems) transpose_item(W, ldw, K, N, g, WT, scr, it, lane);
;     base += nitems;
; __global__ void __launch_bounds__(512, 2) fwd_kernel(Params p) {
;     ...
;         for (int i = 0; i < 4; ++i) transpose_job(w_mem_kv + (size_t)i * D * 512, 512, D, 512, g_mem + i * D, WT + WT_MEM + (size_t)i * 512 * D, scr, base, gwave, gwaves, lane);
.LBB0_55:
	s_cmpk_gt_i32 s50, 0xff
	s_branch .LBB0_19
	s_ashr_i32 s0, s50, 31
	s_lshr_b32 s0, s0, 28
	s_add_i32 s0, s50, s0
	s_ashr_i32 s0, s0, 4
	s_lshl_b32 s40, s0, 6
	s_lshl_b32 s0, s0, 9
	s_lshl_b32 s1, s50, 5
	s_sub_i32 s2, s1, s0
	s_ashr_i32 s3, s2, 31
	s_lshl_b64 s[0:1], s[2:3], 2
	s_add_u32 s0, s38, s0
	s_addc_u32 s1, s39, s1
	s_ashr_i32 s41, s40, 31
	v_mov_b32_e32 v13, s41
	v_or_b32_e32 v12, s40, v2
	v_lshl_add_u64 v[10:11], s[0:1], 0, v[0:1]
	v_or_b32_e32 v9, s40, v4
	v_lshlrev_b64 v[12:13], 2, v[12:13]
	s_mov_b32 s3, 0
	s_mov_b64 s[38:39], s[8:9]
	v_mov_b32_e32 v18, v218
	s_branch .LBB0_58

; __device__ __forceinline__ void transpose_job(const float* W, int ldw, int K, int N, const float* g, bf16_t* WT, float* scr, int& base, int gwave, int gwaves, int lane) {
;     const int nitems = (K / 64) * (N / 32);
;     int start = (gwave - (base % gwaves) + gwaves) % gwaves;
;     int it = start;
;     for (; it + gwaves < nitems; it += 2 * gwaves) transpose_item2(W, ldw, K, N, g, WT, scr, it, it + gwaves, lane);
;     if (it < nitems) transpose_item(W, ldw, K, N, g, WT, scr, it, lane);
;     base += nitems;
; __global__ void __launch_bounds__(512, 2) fwd_kernel(Params p) {
;     ...
;         for (int i = 0; i < 4; ++i) transpose_job(w_out + (size_t)i * D * D, D, D, D, nullptr, WT + WT_OUT + (size_t)i * D * D, scr, base, gwave, gwaves, lane);
.LBB0_76:
	s_lshl_b32 s0, s40, 20
	s_lshl_b64 s[2:3], s[0:1], 2
	s_add_u32 s6, s88, s2
	s_addc_u32 s7, s89, s3
	s_lshl_b32 s0, s40, 21
	s_add_u32 s4, s36, s0
	s_mul_hi_u32 s0, s38, s45
	s_mul_i32 s0, s0, s31
	s_addc_u32 s5, s37, 0
	s_sub_i32 s0, s38, s0
	s_sub_i32 s2, s0, s31
	s_cmp_ge_u32 s0, s31
	s_cselect_b32 s0, s2, s0
	s_sub_i32 s2, s0, s31
	s_cmp_ge_u32 s0, s31
	s_cselect_b32 s0, s2, s0
	s_sub_i32 s0, s11, s0
	s_ashr_i32 s2, s0, 31
	s_abs_i32 s0, s0
	s_mul_hi_u32 s3, s0, s45
	s_mul_i32 s3, s3, s31
	s_sub_i32 s0, s0, s3
	s_sub_i32 s3, s0, s31
	s_cmp_ge_u32 s0, s31
	s_cselect_b32 s0, s3, s0
	s_sub_i32 s3, s0, s31
	s_cmp_ge_u32 s0, s31
	s_cselect_b32 s0, s3, s0
	s_xor_b32 s3, s0, s2
	s_sub_i32 s0, s3, s2
	s_add_i32 s8, s0, s30
	s_cmpk_gt_i32 s8, 0x1ff
	s_branch .LBB0_79
	v_mov_b32_e32 v9, v1
	s_lshl_b32 s3, s3, 5
	s_lshl_b32 s2, s2, 5
	v_lshl_add_u64 v[10:11], s[6:7], 0, v[0:1]
	v_lshl_add_u64 v[12:13], s[4:5], 0, v[8:9]
	s_sub_i32 s41, s3, s2

; __device__ __forceinline__ void transpose_job(const float* W, int ldw, int K, int N, const float* g, bf16_t* WT, float* scr, int& base, int gwave, int gwaves, int lane) {
;     const int nitems = (K / 64) * (N / 32);
;     int start = (gwave - (base % gwaves) + gwaves) % gwaves;
;     int it = start;
;     for (; it + gwaves < nitems; it += 2 * gwaves) transpose_item2(W, ldw, K, N, g, WT, scr, it, it + gwaves, lane);
;     if (it < nitems) transpose_item(W, ldw, K, N, g, WT, scr, it, lane);
;     base += nitems;
; __global__ void __launch_bounds__(512, 2) fwd_kernel(Params p) {
;     ...
;         for (int i = 0; i < 4; ++i) transpose_job(w_out + (size_t)i * D * D, D, D, D, nullptr, WT + WT_OUT + (size_t)i * D * D, scr, base, gwave, gwaves, lane);
.LBB0_79:
	s_cmpk_gt_i32 s0, 0x1ff
	s_branch .LBB0_75
	s_ashr_i32 s2, s0, 31
	s_lshr_b32 s2, s2, 27
	s_add_i32 s2, s0, s2
	s_ashr_i32 s2, s2, 5
	s_lshl_b32 s8, s2, 6
	s_lshl_b32 s2, s2, 10
	s_lshl_b32 s0, s0, 5
	s_sub_i32 s2, s0, s2
	s_ashr_i32 s3, s2, 31
	s_lshl_b64 s[18:19], s[2:3], 2
	s_add_u32 s6, s6, s18
	s_addc_u32 s7, s7, s19
	v_lshl_add_u64 v[10:11], s[6:7], 0, v[0:1]
	v_or_b32_e32 v7, s8, v5
	v_or_b32_e32 v12, s8, v4
	s_mov_b32 s0, 1
	s_mov_b32 s3, 0
	s_mov_b32 s6, 32

; __device__ __forceinline__ void transpose_job(const float* W, int ldw, int K, int N, const float* g, bf16_t* WT, float* scr, int& base, int gwave, int gwaves, int lane) {
;     const int nitems = (K / 64) * (N / 32);
;     int start = (gwave - (base % gwaves) + gwaves) % gwaves;
;     int it = start;
;     for (; it + gwaves < nitems; it += 2 * gwaves) transpose_item2(W, ldw, K, N, g, WT, scr, it, it + gwaves, lane);
;     if (it < nitems) transpose_item(W, ldw, K, N, g, WT, scr, it, lane);
;     base += nitems;
; __global__ void __launch_bounds__(512, 2) fwd_kernel(Params p) {
;     ...
;         for (int i = 0; i < 4; ++i) transpose_job(w_ff1 + (size_t)i * D * DFF, DFF, D, DFF, g_mlp + i * D, WT + WT_FF1 + (size_t)i * DFF * D, scr, base, gwave, gwaves, lane);
.LBB0_86:
	s_lshl_b64 s[0:1], s[8:9], 23
	s_add_u32 s34, s42, s0
	s_mul_hi_u32 s0, s47, s45
	s_mul_i32 s0, s0, s31
	s_addc_u32 s35, s43, s1
	s_sub_i32 s0, s47, s0
	s_sub_i32 s1, s0, s31
	s_cmp_ge_u32 s0, s31
	s_cselect_b32 s0, s1, s0
	s_sub_i32 s1, s0, s31
	s_cmp_ge_u32 s0, s31
	s_cselect_b32 s0, s1, s0
	s_sub_i32 s1, s11, s0
	s_ashr_i32 s0, s1, 31
	s_abs_i32 s1, s1
	s_mul_hi_u32 s2, s1, s45
	s_mul_i32 s2, s2, s31
	s_sub_i32 s1, s1, s2
	s_sub_i32 s2, s1, s31
	s_cmp_ge_u32 s1, s31
	s_cselect_b32 s1, s2, s1
	s_sub_i32 s2, s1, s31
	s_cmp_ge_u32 s1, s31
	s_cselect_b32 s1, s2, s1
	s_xor_b32 s1, s1, s0
	s_sub_i32 s48, s1, s0
	s_add_i32 s2, s48, s30
	s_cmpk_gt_i32 s2, 0x7ff
	s_branch .LBB0_121
	s_lshl_b64 s[2:3], s[8:9], 24
	s_add_u32 s2, s90, s2
	s_addc_u32 s3, s91, s3
	s_lshl_b32 s36, s8, 10
	s_mov_b32 s37, s9
	s_lshl_b64 s[36:37], s[36:37], 2
	s_add_u32 s36, s20, s36
	s_addc_u32 s37, s21, s37
	s_lshl_b32 s1, s1, 5
	s_lshl_b32 s0, s0, 5
	v_lshl_add_u64 v[12:13], s[2:3], 0, v[0:1]
	v_lshl_add_u64 v[14:15], s[34:35], 0, v[8:9]
	s_sub_i32 s49, s1, s0
	s_branch .LBB0_90

; __device__ __forceinline__ void transpose_job(const float* W, int ldw, int K, int N, const float* g, bf16_t* WT, float* scr, int& base, int gwave, int gwaves, int lane) {
;     const int nitems = (K / 64) * (N / 32);
;     int start = (gwave - (base % gwaves) + gwaves) % gwaves;
;     int it = start;
;     for (; it + gwaves < nitems; it += 2 * gwaves) transpose_item2(W, ldw, K, N, g, WT, scr, it, it + gwaves, lane);
;     if (it < nitems) transpose_item(W, ldw, K, N, g, WT, scr, it, lane);
;     base += nitems;
; __global__ void __launch_bounds__(512, 2) fwd_kernel(Params p) {
;     ...
;         for (int i = 0; i < 4; ++i) transpose_job(w_ff1 + (size_t)i * D * DFF, DFF, D, DFF, g_mlp + i * D, WT + WT_FF1 + (size_t)i * DFF * D, scr, base, gwave, gwaves, lane);
.LBB0_121:
	s_cmpk_gt_i32 s48, 0x7ff
	s_branch .LBB0_85
	s_ashr_i32 s0, s48, 31
	s_lshr_b32 s0, s0, 25
	s_add_i32 s0, s48, s0
	s_ashr_i32 s0, s0, 7
	s_lshl_b32 s36, s0, 6
	s_lshl_b32 s0, s0, 12
	s_lshl_b32 s1, s48, 5
	s_sub_i32 s2, s1, s0
	v_or_b32_e32 v12, s36, v154
	v_or_b32_e32 v16, s36, v153
	v_or_b32_e32 v18, s36, v152
	v_or_b32_e32 v20, s36, v151
	v_or_b32_e32 v22, s36, v150
	v_or_b32_e32 v24, s36, v149
	s_waitcnt vmcnt(26)
	v_or_b32_e32 v26, s36, v137
	s_waitcnt vmcnt(10)
	v_or_b32_e32 v30, s36, v4
	s_ashr_i32 s3, s2, 31
	v_ashrrev_i32_e32 v13, 31, v12
	v_ashrrev_i32_e32 v17, 31, v16
	v_ashrrev_i32_e32 v19, 31, v18
	v_ashrrev_i32_e32 v21, 31, v20
	v_ashrrev_i32_e32 v23, 31, v22
	v_ashrrev_i32_e32 v25, 31, v24
	v_ashrrev_i32_e32 v27, 31, v26
	s_waitcnt vmcnt(8)
	v_ashrrev_i32_e32 v31, 31, v30
	s_ashr_i32 s37, s36, 31
	v_lshlrev_b64 v[12:13], 14, v[12:13]
	s_lshl_b64 s[0:1], s[2:3], 2
	v_lshlrev_b64 v[16:17], 14, v[16:17]
	v_lshlrev_b64 v[18:19], 14, v[18:19]
	v_lshlrev_b64 v[20:21], 14, v[20:21]
	v_lshlrev_b64 v[22:23], 14, v[22:23]
	v_lshlrev_b64 v[24:25], 14, v[24:25]
	v_lshlrev_b64 v[26:27], 14, v[26:27]
	v_lshlrev_b64 v[28:29], 14, v[30:31]
	v_mov_b32_e32 v15, s37
	v_or_b32_e32 v14, s36, v2
	v_lshl_add_u64 v[12:13], v[12:13], 0, s[0:1]
	v_lshl_add_u64 v[16:17], v[16:17], 0, s[0:1]
	v_lshl_add_u64 v[18:19], v[18:19], 0, s[0:1]
	v_lshl_add_u64 v[20:21], v[20:21], 0, s[0:1]
	v_lshl_add_u64 v[22:23], v[22:23], 0, s[0:1]
	v_lshl_add_u64 v[24:25], v[24:25], 0, s[0:1]
	v_lshl_add_u64 v[26:27], v[26:27], 0, s[0:1]
	v_lshl_add_u64 v[28:29], v[28:29], 0, s[0:1]
	v_lshl_add_u64 v[12:13], v[10:11], 0, v[12:13]
	v_lshlrev_b64 v[14:15], 2, v[14:15]
	v_lshl_add_u64 v[16:17], v[10:11], 0, v[16:17]
	v_lshl_add_u64 v[18:19], v[10:11], 0, v[18:19]
	v_lshl_add_u64 v[20:21], v[10:11], 0, v[20:21]
	v_lshl_add_u64 v[22:23], v[10:11], 0, v[22:23]
	v_lshl_add_u64 v[24:25], v[10:11], 0, v[24:25]
	v_lshl_add_u64 v[26:27], v[10:11], 0, v[26:27]
	v_lshl_add_u64 v[28:29], v[10:11], 0, v[28:29]
	v_lshlrev_b64 v[30:31], 2, v[30:31]
	s_mov_b64 s[38:39], 0
	s_mov_b64 s[40:41], s[6:7]
	v_mov_b32_e32 v34, v218
	s_branch .LBB0_124

; __device__ __forceinline__ void transpose_job(const float* W, int ldw, int K, int N, const float* g, bf16_t* WT, float* scr, int& base, int gwave, int gwaves, int lane) {
;     const int nitems = (K / 64) * (N / 32);
;     int start = (gwave - (base % gwaves) + gwaves) % gwaves;
;     int it = start;
;     for (; it + gwaves < nitems; it += 2 * gwaves) transpose_item2(W, ldw, K, N, g, WT, scr, it, it + gwaves, lane);
;     if (it < nitems) transpose_item(W, ldw, K, N, g, WT, scr, it, lane);
;     base += nitems;
; __global__ void __launch_bounds__(512, 2) fwd_kernel(Params p) {
;     ...
;         for (int i = 0; i < 4; ++i) transpose_job(w_ff2 + (size_t)i * DFF * D, D, DFF, D, nullptr, WT + WT_FF2 + (size_t)i * D * DFF, scr, base, gwave, gwaves, lane);
.LBB0_142:
	s_lshl_b64 s[2:3], s[0:1], 24
	s_add_u32 s6, s60, s2
	s_addc_u32 s7, s61, s3
	s_lshl_b64 s[2:3], s[0:1], 23
	s_add_u32 s4, s34, s2
	s_mul_hi_u32 s2, s36, s45
	s_mul_i32 s2, s2, s31
	s_addc_u32 s5, s35, s3
	s_sub_i32 s2, s36, s2
	s_sub_i32 s3, s2, s31
	s_cmp_ge_u32 s2, s31
	s_cselect_b32 s2, s3, s2
	s_sub_i32 s3, s2, s31
	s_cmp_ge_u32 s2, s31
	s_cselect_b32 s2, s3, s2
	s_sub_i32 s3, s11, s2
	s_ashr_i32 s2, s3, 31
	s_abs_i32 s3, s3
	s_mul_hi_u32 s8, s3, s45
	s_mul_i32 s8, s8, s31
	s_sub_i32 s3, s3, s8
	s_sub_i32 s8, s3, s31
	s_cmp_ge_u32 s3, s31
	s_cselect_b32 s3, s8, s3
	s_sub_i32 s8, s3, s31
	s_cmp_ge_u32 s3, s31
	s_cselect_b32 s3, s8, s3
	s_xor_b32 s3, s3, s2
	s_sub_i32 s38, s3, s2
	s_add_i32 s8, s38, s30
	s_cmpk_gt_i32 s8, 0x7ff
	s_branch .LBB0_145
	v_mov_b32_e32 v9, v1
	s_lshl_b32 s3, s3, 5
	s_lshl_b32 s2, s2, 5
	v_lshl_add_u64 v[10:11], s[6:7], 0, v[0:1]
	v_lshl_add_u64 v[12:13], s[4:5], 0, v[8:9]
	s_sub_i32 s39, s3, s2

; __device__ __forceinline__ void transpose_job(const float* W, int ldw, int K, int N, const float* g, bf16_t* WT, float* scr, int& base, int gwave, int gwaves, int lane) {
;     const int nitems = (K / 64) * (N / 32);
;     int start = (gwave - (base % gwaves) + gwaves) % gwaves;
;     int it = start;
;     for (; it + gwaves < nitems; it += 2 * gwaves) transpose_item2(W, ldw, K, N, g, WT, scr, it, it + gwaves, lane);
;     if (it < nitems) transpose_item(W, ldw, K, N, g, WT, scr, it, lane);
;     base += nitems;
; __global__ void __launch_bounds__(512, 2) fwd_kernel(Params p) {
;     ...
;         for (int i = 0; i < 4; ++i) transpose_job(w_ff2 + (size_t)i * DFF * D, D, DFF, D, nullptr, WT + WT_FF2 + (size_t)i * D * DFF, scr, base, gwave, gwaves, lane);
.LBB0_145:
	s_cmpk_gt_i32 s38, 0x7ff
	s_branch .LBB0_141
	s_ashr_i32 s2, s38, 31
	s_lshr_b32 s2, s2, 27
	s_add_i32 s2, s38, s2
	s_ashr_i32 s2, s2, 5
	s_lshl_b32 s8, s2, 6
	s_lshl_b32 s2, s2, 10
	s_lshl_b32 s3, s38, 5
	s_sub_i32 s2, s3, s2
	s_ashr_i32 s3, s2, 31
	s_lshl_b64 s[18:19], s[2:3], 2
	s_add_u32 s6, s6, s18
	s_addc_u32 s7, s7, s19
	v_lshl_add_u64 v[10:11], s[6:7], 0, v[0:1]
	v_or_b32_e32 v7, s8, v5
	v_or_b32_e32 v12, s8, v4
	s_mov_b32 s3, 1
	s_mov_b32 s6, 0
	s_mov_b32 s7, 32

; __device__ __forceinline__ void transpose_job(const float* W, int ldw, int K, int N, const float* g, bf16_t* WT, float* scr, int& base, int gwave, int gwaves, int lane) {
;     const int nitems = (K / 64) * (N / 32);
;     int start = (gwave - (base % gwaves) + gwaves) % gwaves;
;     int it = start;
;     for (; it + gwaves < nitems; it += 2 * gwaves) transpose_item2(W, ldw, K, N, g, WT, scr, it, it + gwaves, lane);
;     if (it < nitems) transpose_item(W, ldw, K, N, g, WT, scr, it, lane);
;     base += nitems;
; __global__ void __launch_bounds__(512, 2) fwd_kernel(Params p) {
;     ...
;         for (int j = 0; j < 2; ++j) transpose_job(w_in_pool + (size_t)j * D * D + 768, D, D, 256, g_mix + (2 * j) * D, WT + wt_in(2 * j) + (size_t)768 * D, scr, base, gwave, gwaves, lane);
.LBB0_152:
	s_lshl_b32 s4, s18, 20
	s_lshl_b64 s[2:3], s[4:5], 2
	s_add_u32 s34, s22, s2
	s_addc_u32 s35, s23, s3
	s_lshl_b32 s4, s18, 11
	s_lshl_b64 s[2:3], s[4:5], 2
	s_add_u32 s8, s16, s2
	s_mul_i32 s4, s18, 0x380000
	s_addc_u32 s9, s17, s3
	s_lshl_b64 s[2:3], s[4:5], 1
	s_add_u32 s2, s64, s2
	s_addc_u32 s3, s65, s3
	s_add_u32 s6, s2, 0x180000
	s_mul_hi_u32 s2, s42, s45
	s_mul_i32 s2, s2, s31
	s_addc_u32 s7, s3, 0
	s_sub_i32 s2, s42, s2
	s_sub_i32 s3, s2, s31
	s_cmp_ge_u32 s2, s31
	s_cselect_b32 s2, s3, s2
	s_sub_i32 s3, s2, s31
	s_cmp_ge_u32 s2, s31
	s_cselect_b32 s2, s3, s2
	s_sub_i32 s3, s11, s2
	s_ashr_i32 s2, s3, 31
	s_abs_i32 s3, s3
	s_mul_hi_u32 s4, s3, s45
	s_mul_i32 s4, s4, s31
	s_sub_i32 s3, s3, s4
	s_sub_i32 s4, s3, s31
	s_cmp_ge_u32 s3, s31
	s_cselect_b32 s3, s4, s3
	s_sub_i32 s4, s3, s31
	s_cmp_ge_u32 s3, s31
	s_cselect_b32 s3, s4, s3
	s_xor_b32 s3, s3, s2
	s_sub_i32 s4, s3, s2
	s_add_i32 s19, s4, s30
	s_cmpk_gt_i32 s19, 0x7f
	s_branch .LBB0_187
	v_mov_b32_e32 v9, v1
	s_lshl_b32 s3, s3, 5
	s_lshl_b32 s2, s2, 5
	v_lshl_add_u64 v[6:7], s[34:35], 0, v[0:1]
	v_lshl_add_u64 v[10:11], s[6:7], 0, v[8:9]
	s_sub_i32 s19, s3, s2
	s_branch .LBB0_156

; __device__ __forceinline__ void transpose_job(const float* W, int ldw, int K, int N, const float* g, bf16_t* WT, float* scr, int& base, int gwave, int gwaves, int lane) {
;     const int nitems = (K / 64) * (N / 32);
;     int start = (gwave - (base % gwaves) + gwaves) % gwaves;
;     int it = start;
;     for (; it + gwaves < nitems; it += 2 * gwaves) transpose_item2(W, ldw, K, N, g, WT, scr, it, it + gwaves, lane);
;     if (it < nitems) transpose_item(W, ldw, K, N, g, WT, scr, it, lane);
;     base += nitems;
; __global__ void __launch_bounds__(512, 2) fwd_kernel(Params p) {
;     ...
;         for (int j = 0; j < 2; ++j) transpose_job(w_in_pool + (size_t)j * D * D + 768, D, D, 256, g_mix + (2 * j) * D, WT + wt_in(2 * j) + (size_t)768 * D, scr, base, gwave, gwaves, lane);
.LBB0_187:
	s_xor_b64 s[2:3], s[20:21], -1
	s_cmpk_gt_i32 s4, 0x7f
	s_branch .LBB0_151
	s_ashr_i32 s19, s4, 31
	s_lshr_b32 s19, s19, 29
	s_add_i32 s19, s4, s19
	s_ashr_i32 s19, s19, 3
	s_lshl_b32 s36, s19, 6
	s_lshl_b32 s19, s19, 8
	s_lshl_b32 s4, s4, 5
	s_sub_i32 s20, s4, s19
	s_ashr_i32 s21, s20, 31
	s_lshl_b64 s[38:39], s[20:21], 2
	s_add_u32 s34, s34, s38
	s_mov_b32 s19, s5
	s_addc_u32 s35, s35, s39
	s_ashr_i32 s37, s36, 31
	s_lshl_b64 s[18:19], s[18:19], 13
	s_add_u32 s18, s40, s18
	v_mov_b32_e32 v11, s37
	v_or_b32_e32 v10, s36, v2
	s_addc_u32 s19, s41, s19
	v_lshl_add_u64 v[6:7], s[34:35], 0, v[0:1]
	v_or_b32_e32 v5, s36, v4
	v_lshl_add_u64 v[10:11], v[10:11], 2, s[18:19]
	s_mov_b32 s4, 0
	v_mov_b32_e32 v9, v218
	s_branch .LBB0_190
